# attention K/V rows staged once per workgroup into a 4-slot LDS ring by coalesced DMA (2 rows ahead), fragments read with ds_read_b128; one barrier per key row; on top of E4
# baseline (speedup 1.0000x reference)
; #define LAS __attribute__((address_space(3)))
; __device__ __forceinline__ void attn_phase(const bf16* __restrict__ proj, const bf16* __restrict__ vt, bf16* __restrict__ ya, const float* __restrict__ rpb, int T, int vcu, int G, LAS unsigned char* lds) {
;     ...
;     for (int wt = vcu; wt < 256; wt += G) {
;         const int rgp = wt % nrgp, h = (wt / nrgp) & 7, s = wt / (nrgp * 8), rg = rgp * 2 + (wave >> 2);
;         const LAS float* tbh = tbl + h * 15 * 31;
;         for (int pass = 0; pass < 2; ++pass) {
;             const int i0 = rg * 8 + pass * 4;
;             int rsj[4];
; #pragma unroll
;             for (int j = 0; j < 4; ++j) { int r_ = i0 + j - 4; r_ = r_ < 0 ? 0 : r_; r_ = r_ > rows - 8 ? rows - 8 : r_; rsj[j] = r_; }
;             const int ka0 = rsj[0], ka1 = rsj[3] + 7;
;             const size_t tok0 = (size_t)s * T;
;             bf16x8 qf[4][2];
; #pragma unroll
;             for (int j = 0; j < 4; ++j) { const char* qb = (const char*)(proj + (tok0 + (size_t)(i0 + j) * 64 + q0) * PW + C_Q + h * 64); qf[j][0] = *(const bf16x8*)(qb + qlane); qf[j][1] = *(const bf16x8*)(qb + qlane + 64); }
;             const char* kb = (const char*)(proj + (tok0 + cs) * PW + C_K + h * 64);
;             const char* vb = (const char*)(vt + (size_t)(h * 64) * MC + tok0 + cs);
;             f32x4 o[4][4]; float mrun[4], lrun[4];
; #pragma unroll
;             for (int j = 0; j < 4; ++j) { mrun[j] = -INFINITY; lrun[j] = 0.f;
; #pragma unroll
;                 for (int dt = 0; dt < 4; ++dt) o[j][dt] = (f32x4){0.f, 0.f, 0.f, 0.f}; }
.LBB0_479:
	s_abs_i32 s23, s1
	v_readlane_b32 s5, v253, 19
	s_mul_hi_u32 s24, s23, s5
	s_mul_i32 s25, s24, s85
	s_sub_i32 s25, s23, s25
	s_ashr_i32 s22, s1, 31
	s_add_i32 s30, s24, 1
	s_sub_i32 s31, s25, s85
	s_cmp_ge_u32 s25, s85
	s_cselect_b32 s24, s30, s24
	s_cselect_b32 s25, s31, s25
	s_add_i32 s30, s24, 1
	s_cmp_ge_u32 s25, s85
	s_cselect_b32 s24, s30, s24
	v_readlane_b32 s5, v253, 20
	s_xor_b32 s24, s24, s22
	s_mul_hi_u32 s25, s23, s5
	s_sub_i32 s60, s24, s22
	s_mul_i32 s30, s25, s86
	s_mul_i32 s24, s60, s85
	s_sub_i32 s23, s23, s30
	s_sub_i32 s24, s1, s24
	s_and_b32 s61, s60, 7
	s_add_i32 s30, s25, 1
	s_sub_i32 s31, s23, s86
	s_cmp_ge_u32 s23, s86
	s_cselect_b32 s25, s30, s25
	s_cselect_b32 s23, s31, s23
	s_add_i32 s30, s25, 1
	s_cmp_ge_u32 s23, s86
	s_cselect_b32 s23, s30, s25
	s_xor_b32 s23, s23, s22
	s_sub_i32 s70, s23, s22
	v_readlane_b32 s5, v253, 22
	s_lshl_b32 s80, s24, 4
	s_mul_i32 s24, s70, s5
	s_mul_hi_i32 s25, s70, s5
	v_writelane_b32 v253, s24, 48
	v_writelane_b32 v253, s61, 49
	v_writelane_b32 v253, s0, 54
	s_or_b32 s30, s24, s0
	s_mul_i32 s31, s25, 0x2400
	s_mul_hi_u32 s74, s30, 0x2400
	s_add_i32 s80, s80, s34
	s_or_b64 s[22:23], s[24:25], s[18:19]
	s_lshl_b32 s36, s61, 7
	s_add_i32 s74, s74, s31
	s_mulk_i32 s30, 0x2400
	s_add_u32 s30, s66, s30
	s_addc_u32 s31, s67, s74
	s_add_u32 s30, s30, s36
	s_addc_u32 s31, s31, 0
	s_mul_i32 s71, s61, 0x744
	s_lshl_b32 s61, s61, 22
	v_lshl_add_u64 v[166:167], s[30:31], 0, v[154:155]
	s_lshl_b64 s[30:31], s[22:23], 10
	s_add_u32 s24, s0, s24
	v_lshl_add_u64 v[2:3], v[158:159], 0, s[36:37]
	s_addc_u32 s25, 0, s25
	v_lshl_add_u64 v[168:169], v[2:3], 0, s[30:31]
	s_mulk_i32 s25, 0x2400
	s_mul_hi_u32 s30, s24, 0x2400
	s_mulk_i32 s24, 0x2400
	s_add_i32 s25, s30, s25
	s_or_b32 s24, s24, s36
	v_lshl_add_u64 v[170:171], s[24:25], 0, v[160:161]
	s_mul_i32 s24, s85, 0x7c0
	s_mul_i32 s24, s24, s60
	s_add_i32 s24, s24, s71
	s_mul_i32 s25, s1, 0x7c0
	s_sub_i32 s24, s24, s25
	v_writelane_b32 v253, s24, 47
	s_lshl_b32 s24, s1, 4
	v_readlane_b32 s5, v253, 21
	s_add_i32 s24, s35, s24
	s_mul_i32 s25, s5, s60
	v_readlane_b32 s5, v253, 23
	s_sub_i32 s81, s24, s25
	s_mul_i32 s24, s5, s70
	s_mul_hi_i32 s25, s5, s70
	s_add_u32 s24, s61, s24
	s_addc_u32 s25, 0, s25
	v_lshl_add_u64 v[164:165], v[156:157], 0, s[36:37]
	v_writelane_b32 v253, s71, 46
	v_lshl_add_u64 v[172:173], s[24:25], 0, v[162:163]
	s_mov_b32 s76, 0
	s_mov_b64 s[70:71], -1
.LBB0_480:
	s_or_b32 s74, s76, s80
	s_max_i32 s24, s74, 4
	s_add_i32 s24, s24, -4
	s_or_b32 s30, s74, 3
	s_min_i32 s36, s24, s87
	s_max_i32 s24, s30, 4
	s_add_i32 s24, s24, -4
	s_or_b32 s82, s74, 1
	s_or_b32 s60, s74, 2
	s_min_i32 s89, s24, s87
	s_ashr_i32 s75, s74, 31
	s_ashr_i32 s83, s82, 31
	s_ashr_i32 s61, s60, 31
	s_ashr_i32 s31, s30, 31
	s_add_i32 s89, s89, 7
	v_mov_b32_e32 v5, 0
	s_cmp_gt_i32 s36, s89
	v_mov_b32_e32 v4, v5
	v_mov_b32_e32 v3, v5
	v_mov_b32_e32 v2, v5
	v_mov_b32_e32 v9, v5
	v_mov_b32_e32 v8, v5
	v_mov_b32_e32 v7, v5
	v_mov_b32_e32 v6, v5
	v_mov_b32_e32 v13, v5
	v_mov_b32_e32 v12, v5
	v_mov_b32_e32 v11, v5
	v_mov_b32_e32 v10, v5
	v_mov_b32_e32 v17, v5
	v_mov_b32_e32 v16, v5
	v_mov_b32_e32 v15, v5
	v_mov_b32_e32 v14, v5
	v_mov_b32_e32 v65, v5
	v_mov_b32_e32 v64, v5
	v_mov_b32_e32 v63, v5
	v_mov_b32_e32 v62, v5
	v_mov_b32_e32 v61, v5
	v_mov_b32_e32 v60, v5
	v_mov_b32_e32 v59, v5
	v_mov_b32_e32 v58, v5
	v_mov_b32_e32 v57, v5
	v_mov_b32_e32 v56, v5
	v_mov_b32_e32 v55, v5
	v_mov_b32_e32 v54, v5
	v_mov_b32_e32 v53, v5
	v_mov_b32_e32 v52, v5
	v_mov_b32_e32 v51, v5
	v_mov_b32_e32 v50, v5
	v_mov_b32_e32 v49, v5
	v_mov_b32_e32 v48, v5
	v_mov_b32_e32 v47, v5
	v_mov_b32_e32 v46, v5
	v_mov_b32_e32 v45, v5
	v_mov_b32_e32 v44, v5
	v_mov_b32_e32 v43, v5
	v_mov_b32_e32 v42, v5
	v_mov_b32_e32 v41, v5
	v_mov_b32_e32 v40, v5
	v_mov_b32_e32 v39, v5
	v_mov_b32_e32 v38, v5
	v_mov_b32_e32 v37, v5
	v_mov_b32_e32 v36, v5
	v_mov_b32_e32 v35, v5
	v_mov_b32_e32 v34, v5
	v_mov_b32_e32 v33, v5
	v_mov_b32_e32 v32, v5
	v_mov_b32_e32 v31, v5
	v_mov_b32_e32 v30, v5
	v_mov_b32_e32 v29, v5
	v_mov_b32_e32 v28, v5
	v_mov_b32_e32 v27, v5
	v_mov_b32_e32 v26, v5
	v_mov_b32_e32 v25, v5
	v_mov_b32_e32 v24, v5
	v_mov_b32_e32 v23, v5
	v_mov_b32_e32 v22, v5
	v_mov_b32_e32 v21, v5
	v_mov_b32_e32 v20, v5
	v_mov_b32_e32 v19, v5
	v_mov_b32_e32 v18, v5
	v_mov_b32_e32 v218, v5
	v_mov_b32_e32 v217, v5
	v_mov_b32_e32 v216, v5
	v_mov_b32_e32 v215, v5
	s_cbranch_scc1 .LBB0_559
; __device__ __forceinline__ void attn_phase(const bf16* __restrict__ proj, const bf16* __restrict__ vt, bf16* __restrict__ ya, const float* __restrict__ rpb, int T, int vcu, int G, LAS unsigned char* lds) {
;     ...
;             int rsj[4];
; #pragma unroll
;             for (int j = 0; j < 4; ++j) { int r_ = i0 + j - 4; r_ = r_ < 0 ? 0 : r_; r_ = r_ > rows - 8 ? rows - 8 : r_; rsj[j] = r_; }
;             const int ka0 = rsj[0], ka1 = rsj[3] + 7;
;             const size_t tok0 = (size_t)s * T;
;             bf16x8 qf[4][2];
; #pragma unroll
;             for (int j = 0; j < 4; ++j) { const char* qb = (const char*)(proj + (tok0 + (size_t)(i0 + j) * 64 + q0) * PW + C_Q + h * 64); qf[j][0] = *(const bf16x8*)(qb + qlane); qf[j][1] = *(const bf16x8*)(qb + qlane + 64); }
;             const char* kb = (const char*)(proj + (tok0 + cs) * PW + C_K + h * 64);
;             const char* vb = (const char*)(vt + (size_t)(h * 64) * MC + tok0 + cs);
;             f32x4 o[4][4]; float mrun[4], lrun[4];
; #pragma unroll
;             for (int j = 0; j < 4; ++j) { mrun[j] = -INFINITY; lrun[j] = 0.f;
; #pragma unroll
;                 for (int dt = 0; dt < 4; ++dt) o[j][dt] = (f32x4){0.f, 0.f, 0.f, 0.f}; }
;             bf16x8 kf[2][2]; v4u vf[4];
;             { const char* kp = kb + (size_t)ka0 * 64 * PW * 2;
; #pragma unroll
;               for (int hf = 0; hf < 2; ++hf) { kf[hf][0] = *(const bf16x8*)(kp + (size_t)(4 * hf) * PW * 2 + klane); kf[hf][1] = *(const bf16x8*)(kp + (size_t)(4 * hf) * PW * 2 + klane + 64); }
;             }
;             for (int ka = ka0; ka <= ka1; ++ka) {
;                 bf16x8 kn[2][2];
; #pragma unroll
;                 for (int hf = 0; hf < 2; ++hf) { kn[hf][0] = kf[hf][0]; kn[hf][1] = kf[hf][1]; }
;                 { const char* vp = vb + (size_t)ka * 64 * 2;
; #pragma unroll
;                   for (int dt = 0; dt < 4; ++dt) vf[dt] = *(const v4u*)(vp + (size_t)(16 * dt) * MC * 2 + vlane); }
;                 if (ka < ka1) { const char* kp = kb + (size_t)(ka + 1) * 64 * PW * 2;
; #pragma unroll
;                     for (int hf = 0; hf < 2; ++hf) { kn[hf][0] = *(const bf16x8*)(kp + (size_t)(4 * hf) * PW * 2 + klane); kn[hf][1] = *(const bf16x8*)(kp + (size_t)(4 * hf) * PW * 2 + klane + 64); } }
	s_max_i32 s24, s82, 4
	s_add_i32 s24, s24, -4
	s_min_i32 s77, s24, s87
	s_max_i32 s24, s60, 4
	s_add_i32 s24, s24, -4
	s_min_i32 s78, s24, s87
	s_lshl_b64 s[24:25], s[74:75], 6
	s_add_u32 s24, s24, s22
	s_addc_u32 s25, s25, s23
	s_mul_i32 s79, s25, 0x2400
	v_mad_u64_u32 v[2:3], s[24:25], s24, v231, v[164:165]
	s_lshl_b64 s[24:25], s[82:83], 6
	s_add_u32 s24, s24, s22
	v_add_u32_e32 v3, s79, v3
	s_addc_u32 s25, s25, s23
	global_load_dwordx4 v[66:69], v[2:3], off
	global_load_dwordx4 v[70:73], v[2:3], off offset:64
	s_mul_i32 s79, s25, 0x2400
	v_mad_u64_u32 v[2:3], s[24:25], s24, v231, v[164:165]
	s_lshl_b64 s[24:25], s[60:61], 6
	s_add_u32 s24, s24, s22
	v_add_u32_e32 v3, s79, v3
	s_addc_u32 s25, s25, s23
	global_load_dwordx4 v[74:77], v[2:3], off
	global_load_dwordx4 v[78:81], v[2:3], off offset:64
	s_mul_i32 s79, s25, 0x2400
	v_mad_u64_u32 v[2:3], s[24:25], s24, v231, v[164:165]
	s_lshl_b64 s[24:25], s[30:31], 6
	s_add_u32 s24, s24, s22
	v_add_u32_e32 v3, s79, v3
	s_addc_u32 s25, s25, s23
	global_load_dwordx4 v[82:85], v[2:3], off
	global_load_dwordx4 v[86:89], v[2:3], off offset:64
	s_mul_i32 s79, s25, 0x2400
	v_mad_u64_u32 v[2:3], s[24:25], s24, v231, v[164:165]
	v_add_u32_e32 v3, s79, v3
	global_load_dwordx4 v[90:93], v[2:3], off
	global_load_dwordx4 v[94:97], v[2:3], off offset:64
	s_mul_i32 s24, s74, 0xffffff84
	v_readlane_b32 s25, v253, 46
	s_nop 3
	s_add_i32 s24, s24, s25
	v_add_u32_e32 v219, s24, v1
	v_add_u32_e32 v220, s24, v178
	v_add_u32_e32 v221, s24, v179
	v_add_u32_e32 v233, s24, v186
	v_add_u32_e32 v234, s24, v187
	v_add_u32_e32 v235, s24, v188
	v_add_u32_e32 v236, s24, v189
	v_add_u32_e32 v237, s24, v190
	s_mul_i32 s24, s76, 0xffffff84
	v_readlane_b32 s25, v253, 47
	s_nop 3
	s_add_i32 s24, s24, s25
	v_add_u32_e32 v238, s24, v191
	v_add_u32_e32 v239, s24, v192
	v_add_u32_e32 v240, s24, v193
	v_add_u32_e32 v241, s24, v194
	v_add_u32_e32 v242, s24, v195
	v_add_u32_e32 v243, s24, v196
	v_add_u32_e32 v244, s24, v197
	v_add_u32_e32 v245, s24, v198
	s_add_i32 s24, s81, s76
	s_max_i32 s24, s24, 4
	s_add_i32 s24, s24, -4
	s_min_i32 s24, s24, s87
	s_sub_i32 s92, s36, s24
	s_lshl_b64 s[24:25], s[36:37], 7
	v_mov_b32_e32 v215, 0
	v_mov_b32_e32 v229, 0x260
	v_mov_b32_e32 v228, 0x3727c5ac
	s_mov_b32 s90, 0
	s_mul_i32 s91, s36, 0x7c
	s_sub_i32 s93, s36, s78
	s_sub_i32 s94, s36, s77
	v_mov_b32_e32 v246, 0xff800000
	v_mov_b32_e32 v247, 0xff800000
	v_mov_b32_e32 v248, 0xff800000
	v_mov_b32_e32 v249, 0xff800000
	v_writelane_b32 v253, s28, 50
	v_writelane_b32 v253, s29, 51
	v_writelane_b32 v253, s62, 52
	v_writelane_b32 v253, s63, 53
	s_andn2_b32 s24, s74, 8
	s_max_i32 s24, s24, 4
	s_add_i32 s24, s24, -4
	s_min_i32 s77, s24, s87
	s_or_b32 s24, s74, 11
	s_max_i32 s24, s24, 4
	s_add_i32 s24, s24, -4
	s_min_i32 s24, s24, s87
	s_add_i32 s78, s24, 7
	v_readlane_b32 s24, v253, 48
	v_readlane_b32 s25, v253, 49
	s_nop 3
	s_lshl_b32 s79, s77, 6
	s_add_i32 s79, s79, s24
	s_mul_i32 s28, s79, 0x2400
	s_mul_hi_u32 s29, s79, 0x2400
	s_lshl_b32 s24, s25, 7
	s_add_i32 s24, s24, 0x8000400
	s_add_u32 s28, s28, s24
	s_addc_u32 s29, s29, 0
	s_add_u32 s28, s28, s58
	s_addc_u32 s29, s29, s59
	s_lshl_b32 s62, s25, 22
	s_lshl_b32 s24, s79, 1
	s_add_i32 s62, s62, s24
	s_add_i32 s62, s62, 0x1a000000
	s_add_u32 s62, s62, s58
	s_addc_u32 s63, s59, 0
	v_lshrrev_b32_e32 v102, 3, v222
	v_and_b32_e32 v103, 7, v222
	v_lshlrev_b32_e32 v103, 4, v103
	v_mul_u32_u24_e32 v98, 0x2400, v102
	v_add_u32_e32 v98, v98, v103
	v_lshl_add_u32 v99, v102, 16, v103
	v_lshrrev_b32_e32 v102, 6, v222
	v_lshlrev_b32_e32 v102, 10, v102
	v_add_u32_e32 v102, 0x4000, v102
	v_readlane_b32 s24, v253, 54
	v_readfirstlane_b32 s79, v102
	v_and_b32_e32 v102, 15, v224
	v_lshrrev_b32_e32 v103, 4, v224
	v_lshrrev_b32_e32 v104, 2, v102
	v_and_b32_e32 v105, 3, v102
	v_lshl_add_u32 v104, v104, 3, v105
	v_add_u32_e32 v104, s24, v104
	v_lshlrev_b32_e32 v100, 7, v104
	v_lshl_add_u32 v100, v103, 4, v100
	v_lshlrev_b32_e32 v101, 7, v102
	v_lshl_add_u32 v101, v103, 4, v101
	s_lshl_b32 s25, s24, 1
	v_add_u32_e32 v101, s25, v101
	v_add_u32_e32 v101, 0x2000, v101
	s_and_b32 s25, s77, 3
	s_lshl_b32 s25, s25, 14
	s_add_i32 s25, s25, s79
	s_mov_b32 m0, s25
	s_nop 0
	global_load_lds_dwordx4 v98, s[28:29]
	s_add_i32 m0, s25, 0x2000
	s_nop 0
	global_load_lds_dwordx4 v99, s[62:63]
	s_add_u32 s28, s28, 0x90000
	s_addc_u32 s29, s29, 0
	s_add_u32 s62, s62, 0x80
	s_addc_u32 s63, s63, 0
	s_add_i32 s25, s77, 1
	s_and_b32 s25, s25, 3
	s_lshl_b32 s25, s25, 14
	s_add_i32 s25, s25, s79
	s_mov_b32 m0, s25
	s_nop 0
	global_load_lds_dwordx4 v98, s[28:29]
	s_add_i32 m0, s25, 0x2000
	s_nop 0
	global_load_lds_dwordx4 v99, s[62:63]
	s_add_u32 s28, s28, 0x90000
	s_addc_u32 s29, s29, 0
	s_add_u32 s62, s62, 0x80
	s_addc_u32 s63, s63, 0
.Lattn_step:
	s_add_i32 s24, s77, 2
	s_cmp_gt_i32 s24, s78
	s_cbranch_scc1 .Lattn_nodma
	s_and_b32 s25, s24, 3
	s_lshl_b32 s25, s25, 14
	s_add_i32 s25, s25, s79
	s_mov_b32 m0, s25
	s_nop 0
	global_load_lds_dwordx4 v98, s[28:29]
	s_add_i32 m0, s25, 0x2000
	s_nop 0
	global_load_lds_dwordx4 v99, s[62:63]
	s_add_u32 s28, s28, 0x90000
	s_addc_u32 s29, s29, 0
	s_add_u32 s62, s62, 0x80
	s_addc_u32 s63, s63, 0
	s_waitcnt vmcnt(4)
	s_branch .Lattn_sync

; #define LAS __attribute__((address_space(3)))
; __device__ __forceinline__ void attn_phase(const bf16* __restrict__ proj, const bf16* __restrict__ vt, bf16* __restrict__ ya, const float* __restrict__ rpb, int T, int vcu, int G, LAS unsigned char* lds) {
;     ...
;             for (int ka = ka0; ka <= ka1; ++ka) {
;                 bf16x8 kn[2][2];
; #pragma unroll
;                 for (int hf = 0; hf < 2; ++hf) { kn[hf][0] = kf[hf][0]; kn[hf][1] = kf[hf][1]; }
;                 { const char* vp = vb + (size_t)ka * 64 * 2;
; #pragma unroll
;                   for (int dt = 0; dt < 4; ++dt) vf[dt] = *(const v4u*)(vp + (size_t)(16 * dt) * MC * 2 + vlane); }
;                 if (ka < ka1) { const char* kp = kb + (size_t)(ka + 1) * 64 * PW * 2;
; #pragma unroll
;                     for (int hf = 0; hf < 2; ++hf) { kn[hf][0] = *(const bf16x8*)(kp + (size_t)(4 * hf) * PW * 2 + klane); kn[hf][1] = *(const bf16x8*)(kp + (size_t)(4 * hf) * PW * 2 + klane + 64); } }
; #pragma unroll
;                 for (int j = 0; j < 4; ++j) { const int kr = ka - rsj[j];
;                     if (kr >= 0 && kr < 8) {
;                         f32x4 st[2];
; #pragma unroll
;                         for (int hf = 0; hf < 2; ++hf) { const f32x4 t = __builtin_amdgcn_mfma_f32_16x16x32_bf16(kf[hf][0], qf[j][0], (f32x4){0.f, 0.f, 0.f, 0.f}, 0, 0, 0);
;                             st[hf] = __builtin_amdgcn_mfma_f32_16x16x32_bf16(kf[hf][1], qf[j][1], t, 0, 0, 0); }
;                         const LAS float* tb = tbh + (ka - i0 - j + 7) * 31;
;                         float mloc = -INFINITY;
; #pragma unroll
;                         for (int hf = 0; hf < 2; ++hf)
; #pragma unroll
;                             for (int e = 0; e < 4; ++e) { const unsigned dc = ((hf == 0 ? dpack0 : dpack1) >> (8 * e)) & 0xffu; const float b = tb[dc];
;                                 const float v = ((vmask >> (hf * 4 + e)) & 1u) ? st[hf][e] * SC + b : -INFINITY; st[hf][e] = v; mloc = fmaxf(mloc, v); }
;                         mloc = fmaxf(mloc, __shfl_xor(mloc, 16)); mloc = fmaxf(mloc, __shfl_xor(mloc, 32));
;                         const float mnew = fmaxf(mrun[j], mloc), alpha = __builtin_amdgcn_exp2f(mrun[j] - mnew); mrun[j] = mnew;
;                         float p[8], psum = 0.f;
; #pragma unroll
;                         for (int hf = 0; hf < 2; ++hf)
; #pragma unroll
.Lattn_sync:
	s_barrier
	s_cmp_lt_i32 s77, s36
	s_cbranch_scc1 .Lattn_skip
	s_cmp_gt_i32 s77, s89
	s_cbranch_scc1 .Lattn_skip
	s_and_b32 s24, s77, 3
	s_lshl_b32 s24, s24, 14
	s_add_i32 s24, s24, 0x4000
	v_add_u32_e32 v102, s24, v100
	v_add_u32_e32 v103, s24, v101
	ds_read_b128 v[118:121], v102
	ds_read_b128 v[122:125], v102 offset:64
	ds_read_b128 v[126:129], v102 offset:512
	ds_read_b128 v[110:113], v102 offset:576
	ds_read_b128 v[142:145], v103
	ds_read_b128 v[134:137], v103 offset:2048
	ds_read_b128 v[138:141], v103 offset:4096
	ds_read_b128 v[130:133], v103 offset:6144
	s_waitcnt lgkmcnt(0)
	s_cmp_gt_u32 s90, 7
	s_cbranch_scc1 .LBB0_502
.LBB0_485:
	v_add_u32_e32 v251, s91, v237
	v_add_u32_e32 v250, s91, v236
	v_add_u32_e32 v227, s91, v235
	v_add_u32_e32 v226, s91, v234
	v_add_u32_e32 v199, s91, v233
	v_add_u32_e32 v212, s91, v221
	v_add_u32_e32 v213, s91, v220
	v_add_u32_e32 v214, s91, v219
	ds_read_b32 v251, v251
	ds_read_b32 v250, v250
	ds_read_b32 v227, v227
	ds_read_b32 v226, v226
	ds_read_b32 v199, v199
	ds_read_b32 v212, v212
	ds_read_b32 v213, v213
	ds_read_b32 v214, v214
	v_mfma_f32_16x16x32_bf16 v[146:149], v[118:121], v[66:69], 0
	v_mfma_f32_16x16x32_bf16 v[150:153], v[122:125], v[70:73], v[146:149]
	v_mfma_f32_16x16x32_bf16 v[146:149], v[126:129], v[66:69], 0
	v_mfma_f32_16x16x32_bf16 v[146:149], v[110:113], v[70:73], v[146:149]
	v_mov_b32_e32 v184, 0xff800000
	s_nop 6
	s_waitcnt lgkmcnt(0)
	v_fmamk_f32 v150, v150, 0x3e38aa3b, v251
	v_fmamk_f32 v151, v151, 0x3e38aa3b, v250
	v_fmamk_f32 v152, v152, 0x3e38aa3b, v227
	v_fmamk_f32 v153, v153, 0x3e38aa3b, v226
	v_fmamk_f32 v146, v146, 0x3e38aa3b, v199
	v_fmamk_f32 v147, v147, 0x3e38aa3b, v212
	v_fmamk_f32 v148, v148, 0x3e38aa3b, v213
	v_fmamk_f32 v149, v149, 0x3e38aa3b, v214
	v_cndmask_b32_e64 v150, v184, v150, s[38:39]
	v_cndmask_b32_e64 v151, v184, v151, s[40:41]
	v_cndmask_b32_e64 v152, v184, v152, s[42:43]
	v_cndmask_b32_e64 v153, v184, v153, s[44:45]
	v_cndmask_b32_e64 v146, v184, v146, s[46:47]
	v_cndmask_b32_e64 v147, v184, v147, s[48:49]
	v_cndmask_b32_e64 v148, v184, v148, s[50:51]
	v_cndmask_b32_e64 v149, v184, v149, s[52:53]
	v_max3_f32 v225, v150, v151, v152
	v_max3_f32 v225, v225, v153, v146
	v_max3_f32 v225, v225, v147, v148
	v_max_f32_e32 v225, v225, v149
	v_mov_b32_e32 v226, v225
	s_nop 1
	v_permlane16_swap_b32_e32 v225, v226
	v_max_f32_e32 v225, v225, v226
	v_mov_b32_e32 v226, v225
	s_nop 1
	v_permlane32_swap_b32_e32 v225, v226
	v_max3_f32 v225, v249, v225, v226
	v_sub_f32_e32 v250, v249, v225
	v_sub_f32_e32 v150, v150, v225
	v_sub_f32_e32 v151, v151, v225
	v_sub_f32_e32 v152, v152, v225
	v_sub_f32_e32 v153, v153, v225
	v_sub_f32_e32 v146, v146, v225
	v_sub_f32_e32 v147, v147, v225
	v_sub_f32_e32 v148, v148, v225
	v_sub_f32_e32 v149, v149, v225
	v_exp_f32_e32 v250, v250
	v_exp_f32_e32 v150, v150
	v_exp_f32_e32 v151, v151
	v_exp_f32_e32 v152, v152
	v_exp_f32_e32 v153, v153
	v_exp_f32_e32 v146, v146
	v_exp_f32_e32 v147, v147
	v_exp_f32_e32 v148, v148
	v_exp_f32_e32 v149, v149
	v_mov_b32_e32 v249, v225
	v_add_f32_e32 v226, v150, v151
	v_add_f32_e32 v226, v226, v152
	v_add_f32_e32 v226, v226, v153
	v_add_f32_e32 v226, v226, v146
	v_add_f32_e32 v226, v226, v147
	v_add_f32_e32 v226, v226, v148
	v_add_f32_e32 v226, v226, v149
	v_fma_f32 v218, v218, v250, v226
	v_pk_mul_f32 v[64:65], v[64:65], v[250:251] op_sel_hi:[1,0]
	v_pk_mul_f32 v[62:63], v[62:63], v[250:251] op_sel_hi:[1,0]
	v_pk_mul_f32 v[60:61], v[60:61], v[250:251] op_sel_hi:[1,0]
	v_pk_mul_f32 v[58:59], v[58:59], v[250:251] op_sel_hi:[1,0]
	v_pk_mul_f32 v[56:57], v[56:57], v[250:251] op_sel_hi:[1,0]
	v_pk_mul_f32 v[54:55], v[54:55], v[250:251] op_sel_hi:[1,0]
	v_pk_mul_f32 v[52:53], v[52:53], v[250:251] op_sel_hi:[1,0]
	v_pk_mul_f32 v[50:51], v[50:51], v[250:251] op_sel_hi:[1,0]
	v_cvt_pk_bf16_f32 v150, v150, v151
	v_cvt_pk_bf16_f32 v151, v152, v153
	v_cvt_pk_bf16_f32 v152, v146, v147
	v_cvt_pk_bf16_f32 v153, v148, v149
	s_nop 1
	v_mfma_f32_16x16x32_bf16 v[62:65], v[142:145], v[150:153], v[62:65]
	v_mfma_f32_16x16x32_bf16 v[58:61], v[134:137], v[150:153], v[58:61]
	v_mfma_f32_16x16x32_bf16 v[54:57], v[138:141], v[150:153], v[54:57]
	v_mfma_f32_16x16x32_bf16 v[50:53], v[130:133], v[150:153], v[50:53]

; #define LAS __attribute__((address_space(3)))
; __device__ __forceinline__ void attn_phase(const bf16* __restrict__ proj, const bf16* __restrict__ vt, bf16* __restrict__ ya, const float* __restrict__ rpb, int T, int vcu, int G, LAS unsigned char* lds) {
;     ...
;                 for (int j = 0; j < 4; ++j) { const int kr = ka - rsj[j];
;                     if (kr >= 0 && kr < 8) {
;                         f32x4 st[2];
; #pragma unroll
;                         for (int hf = 0; hf < 2; ++hf) { const f32x4 t = __builtin_amdgcn_mfma_f32_16x16x32_bf16(kf[hf][0], qf[j][0], (f32x4){0.f, 0.f, 0.f, 0.f}, 0, 0, 0);
;                             st[hf] = __builtin_amdgcn_mfma_f32_16x16x32_bf16(kf[hf][1], qf[j][1], t, 0, 0, 0); }
;                         const LAS float* tb = tbh + (ka - i0 - j + 7) * 31;
;                         float mloc = -INFINITY;
; #pragma unroll
;                         for (int hf = 0; hf < 2; ++hf)
; #pragma unroll
;                             for (int e = 0; e < 4; ++e) { const unsigned dc = ((hf == 0 ? dpack0 : dpack1) >> (8 * e)) & 0xffu; const float b = tb[dc];
;                                 const float v = ((vmask >> (hf * 4 + e)) & 1u) ? st[hf][e] * SC + b : -INFINITY; st[hf][e] = v; mloc = fmaxf(mloc, v); }
;                         mloc = fmaxf(mloc, __shfl_xor(mloc, 16)); mloc = fmaxf(mloc, __shfl_xor(mloc, 32));
;                         const float mnew = fmaxf(mrun[j], mloc), alpha = __builtin_amdgcn_exp2f(mrun[j] - mnew); mrun[j] = mnew;
;                         float p[8], psum = 0.f;
; #pragma unroll
;                         for (int hf = 0; hf < 2; ++hf)
; #pragma unroll
;                             for (int e = 0; e < 4; ++e) { p[hf * 4 + e] = __builtin_amdgcn_exp2f(st[hf][e] - mnew); psum += p[hf * 4 + e]; }
;                         lrun[j] = lrun[j] * alpha + psum;
;                         v4u w; w.x = cvt_pk_bf16(p[0], p[1]); w.y = cvt_pk_bf16(p[2], p[3]); w.z = cvt_pk_bf16(p[4], p[5]); w.w = cvt_pk_bf16(p[6], p[7]);
;                         const bf16x8 pk = __builtin_bit_cast(bf16x8, w);
; #pragma unroll
;                         for (int dt = 0; dt < 4; ++dt) o[j][dt] = __builtin_amdgcn_mfma_f32_16x16x32_bf16(__builtin_bit_cast(bf16x8, vf[dt]), pk, o[j][dt] * alpha, 0, 0, 0);
;                     } }
.LBB0_505:
	v_add_u32_e32 v251, s91, v245
	v_add_u32_e32 v250, s91, v244
	v_add_u32_e32 v227, s91, v243
	v_add_u32_e32 v226, s91, v242
	v_add_u32_e32 v199, s91, v241
	v_add_u32_e32 v212, s91, v240
	v_add_u32_e32 v213, s91, v239
	v_add_u32_e32 v214, s91, v238
	ds_read_b32 v251, v251 offset:248
	ds_read_b32 v250, v250 offset:248
	ds_read_b32 v227, v227 offset:248
	ds_read_b32 v226, v226 offset:248
	ds_read_b32 v199, v199 offset:248
	ds_read_b32 v212, v212 offset:248
	ds_read_b32 v213, v213 offset:248
	ds_read_b32 v214, v214 offset:248
	v_mfma_f32_16x16x32_bf16 v[146:149], v[118:121], v[74:77], 0
	v_mfma_f32_16x16x32_bf16 v[150:153], v[122:125], v[78:81], v[146:149]
	v_mfma_f32_16x16x32_bf16 v[146:149], v[126:129], v[74:77], 0
	v_mfma_f32_16x16x32_bf16 v[146:149], v[110:113], v[78:81], v[146:149]
	v_mov_b32_e32 v184, 0xff800000
	s_nop 6
	s_waitcnt lgkmcnt(0)
	v_fmamk_f32 v150, v150, 0x3e38aa3b, v251
	v_fmamk_f32 v151, v151, 0x3e38aa3b, v250
	v_fmamk_f32 v152, v152, 0x3e38aa3b, v227
	v_fmamk_f32 v153, v153, 0x3e38aa3b, v226
	v_fmamk_f32 v146, v146, 0x3e38aa3b, v199
	v_fmamk_f32 v147, v147, 0x3e38aa3b, v212
	v_fmamk_f32 v148, v148, 0x3e38aa3b, v213
	v_fmamk_f32 v149, v149, 0x3e38aa3b, v214
	v_cndmask_b32_e64 v150, v184, v150, s[38:39]
	v_cndmask_b32_e64 v151, v184, v151, s[40:41]
	v_cndmask_b32_e64 v152, v184, v152, s[42:43]
	v_cndmask_b32_e64 v153, v184, v153, s[44:45]
	v_cndmask_b32_e64 v146, v184, v146, s[46:47]
	v_cndmask_b32_e64 v147, v184, v147, s[48:49]
	v_cndmask_b32_e64 v148, v184, v148, s[50:51]
	v_cndmask_b32_e64 v149, v184, v149, s[52:53]
	v_max3_f32 v225, v150, v151, v152
	v_max3_f32 v225, v225, v153, v146
	v_max3_f32 v225, v225, v147, v148
	v_max_f32_e32 v225, v225, v149
	v_mov_b32_e32 v226, v225
	s_nop 1
	v_permlane16_swap_b32_e32 v225, v226
	v_max_f32_e32 v225, v225, v226
	v_mov_b32_e32 v226, v225
	s_nop 1
	v_permlane32_swap_b32_e32 v225, v226
	v_max3_f32 v225, v248, v225, v226
	v_sub_f32_e32 v250, v248, v225
	v_sub_f32_e32 v150, v150, v225
	v_sub_f32_e32 v151, v151, v225
	v_sub_f32_e32 v152, v152, v225
	v_sub_f32_e32 v153, v153, v225
	v_sub_f32_e32 v146, v146, v225
	v_sub_f32_e32 v147, v147, v225
	v_sub_f32_e32 v148, v148, v225
	v_sub_f32_e32 v149, v149, v225
	v_exp_f32_e32 v250, v250
	v_exp_f32_e32 v150, v150
	v_exp_f32_e32 v151, v151
	v_exp_f32_e32 v152, v152
	v_exp_f32_e32 v153, v153
	v_exp_f32_e32 v146, v146
	v_exp_f32_e32 v147, v147
	v_exp_f32_e32 v148, v148
	v_exp_f32_e32 v149, v149
	v_mov_b32_e32 v248, v225
	v_add_f32_e32 v226, v150, v151
	v_add_f32_e32 v226, v226, v152
	v_add_f32_e32 v226, v226, v153
	v_add_f32_e32 v226, v226, v146
	v_add_f32_e32 v226, v226, v147
	v_add_f32_e32 v226, v226, v148
	v_add_f32_e32 v226, v226, v149
	v_fma_f32 v217, v217, v250, v226
	v_pk_mul_f32 v[48:49], v[48:49], v[250:251] op_sel_hi:[1,0]
	v_pk_mul_f32 v[46:47], v[46:47], v[250:251] op_sel_hi:[1,0]
	v_pk_mul_f32 v[44:45], v[44:45], v[250:251] op_sel_hi:[1,0]
	v_pk_mul_f32 v[42:43], v[42:43], v[250:251] op_sel_hi:[1,0]
	v_pk_mul_f32 v[40:41], v[40:41], v[250:251] op_sel_hi:[1,0]
	v_pk_mul_f32 v[38:39], v[38:39], v[250:251] op_sel_hi:[1,0]
	v_pk_mul_f32 v[36:37], v[36:37], v[250:251] op_sel_hi:[1,0]
	v_pk_mul_f32 v[34:35], v[34:35], v[250:251] op_sel_hi:[1,0]
	v_cvt_pk_bf16_f32 v150, v150, v151
	v_cvt_pk_bf16_f32 v151, v152, v153
	v_cvt_pk_bf16_f32 v152, v146, v147
	v_cvt_pk_bf16_f32 v153, v148, v149
	s_nop 1
	v_mfma_f32_16x16x32_bf16 v[46:49], v[142:145], v[150:153], v[46:49]
	v_mfma_f32_16x16x32_bf16 v[42:45], v[134:137], v[150:153], v[42:45]
	v_mfma_f32_16x16x32_bf16 v[38:41], v[138:141], v[150:153], v[38:41]
	v_mfma_f32_16x16x32_bf16 v[34:37], v[130:133], v[150:153], v[34:37]
	s_add_i32 s24, s93, s90
	s_cmp_gt_u32 s24, 7
	s_cbranch_scc1 .LBB0_504
.LBB0_522:
	v_add_u32_e32 v251, s91, v245
	v_add_u32_e32 v250, s91, v244
	v_add_u32_e32 v227, s91, v243
	v_add_u32_e32 v226, s91, v242
	v_add_u32_e32 v199, s91, v241
	v_add_u32_e32 v212, s91, v240
	v_add_u32_e32 v213, s91, v239
	v_add_u32_e32 v214, s91, v238
	ds_read_b32 v251, v251 offset:124
	ds_read_b32 v250, v250 offset:124
	ds_read_b32 v227, v227 offset:124
	ds_read_b32 v226, v226 offset:124
	ds_read_b32 v199, v199 offset:124
	ds_read_b32 v212, v212 offset:124
	ds_read_b32 v213, v213 offset:124
	ds_read_b32 v214, v214 offset:124
	v_mfma_f32_16x16x32_bf16 v[146:149], v[118:121], v[82:85], 0
	v_mfma_f32_16x16x32_bf16 v[150:153], v[122:125], v[86:89], v[146:149]
	v_mfma_f32_16x16x32_bf16 v[146:149], v[126:129], v[82:85], 0
	v_mfma_f32_16x16x32_bf16 v[146:149], v[110:113], v[86:89], v[146:149]
	v_mov_b32_e32 v184, 0xff800000
	s_nop 6
	s_waitcnt lgkmcnt(0)
; __device__ __forceinline__ unsigned cvt_pk_bf16(float lo, float hi) { unsigned r; asm volatile("v_cvt_pk_bf16_f32 %0, %1, %2" : "=v"(r) : "v"(lo), "v"(hi)); return r; }
; #define LAS __attribute__((address_space(3)))
; __device__ __forceinline__ void attn_phase(const bf16* __restrict__ proj, const bf16* __restrict__ vt, bf16* __restrict__ ya, const float* __restrict__ rpb, int T, int vcu, int G, LAS unsigned char* lds) {
;     ...
;                         const LAS float* tb = tbh + (ka - i0 - j + 7) * 31;
;                         float mloc = -INFINITY;
; #pragma unroll
;                         for (int hf = 0; hf < 2; ++hf)
; #pragma unroll
;                             for (int e = 0; e < 4; ++e) { const unsigned dc = ((hf == 0 ? dpack0 : dpack1) >> (8 * e)) & 0xffu; const float b = tb[dc];
;                                 const float v = ((vmask >> (hf * 4 + e)) & 1u) ? st[hf][e] * SC + b : -INFINITY; st[hf][e] = v; mloc = fmaxf(mloc, v); }
;                         mloc = fmaxf(mloc, __shfl_xor(mloc, 16)); mloc = fmaxf(mloc, __shfl_xor(mloc, 32));
;                         const float mnew = fmaxf(mrun[j], mloc), alpha = __builtin_amdgcn_exp2f(mrun[j] - mnew); mrun[j] = mnew;
;                         float p[8], psum = 0.f;
; #pragma unroll
;                         for (int hf = 0; hf < 2; ++hf)
; #pragma unroll
;                             for (int e = 0; e < 4; ++e) { p[hf * 4 + e] = __builtin_amdgcn_exp2f(st[hf][e] - mnew); psum += p[hf * 4 + e]; }
;                         lrun[j] = lrun[j] * alpha + psum;
;                         v4u w; w.x = cvt_pk_bf16(p[0], p[1]); w.y = cvt_pk_bf16(p[2], p[3]); w.z = cvt_pk_bf16(p[4], p[5]); w.w = cvt_pk_bf16(p[6], p[7]);
;                         const bf16x8 pk = __builtin_bit_cast(bf16x8, w);
; #pragma unroll
;                         for (int dt = 0; dt < 4; ++dt) o[j][dt] = __builtin_amdgcn_mfma_f32_16x16x32_bf16(__builtin_bit_cast(bf16x8, vf[dt]), pk, o[j][dt] * alpha, 0, 0, 0);
;                     } }
	v_fmamk_f32 v150, v150, 0x3e38aa3b, v251
	v_fmamk_f32 v151, v151, 0x3e38aa3b, v250
	v_fmamk_f32 v152, v152, 0x3e38aa3b, v227
	v_fmamk_f32 v153, v153, 0x3e38aa3b, v226
	v_fmamk_f32 v146, v146, 0x3e38aa3b, v199
	v_fmamk_f32 v147, v147, 0x3e38aa3b, v212
	v_fmamk_f32 v148, v148, 0x3e38aa3b, v213
	v_fmamk_f32 v149, v149, 0x3e38aa3b, v214
	v_cndmask_b32_e64 v150, v184, v150, s[38:39]
	v_cndmask_b32_e64 v151, v184, v151, s[40:41]
	v_cndmask_b32_e64 v152, v184, v152, s[42:43]
	v_cndmask_b32_e64 v153, v184, v153, s[44:45]
	v_cndmask_b32_e64 v146, v184, v146, s[46:47]
	v_cndmask_b32_e64 v147, v184, v147, s[48:49]
	v_cndmask_b32_e64 v148, v184, v148, s[50:51]
	v_cndmask_b32_e64 v149, v184, v149, s[52:53]
	v_max3_f32 v225, v150, v151, v152
	v_max3_f32 v225, v225, v153, v146
	v_max3_f32 v225, v225, v147, v148
	v_max_f32_e32 v225, v225, v149
	v_mov_b32_e32 v226, v225
	s_nop 1
	v_permlane16_swap_b32_e32 v225, v226
	v_max_f32_e32 v225, v225, v226
	v_mov_b32_e32 v226, v225
	s_nop 1
	v_permlane32_swap_b32_e32 v225, v226
	v_max3_f32 v225, v247, v225, v226
	v_sub_f32_e32 v250, v247, v225
	v_sub_f32_e32 v150, v150, v225
	v_sub_f32_e32 v151, v151, v225
	v_sub_f32_e32 v152, v152, v225
	v_sub_f32_e32 v153, v153, v225
	v_sub_f32_e32 v146, v146, v225
	v_sub_f32_e32 v147, v147, v225
	v_sub_f32_e32 v148, v148, v225
	v_sub_f32_e32 v149, v149, v225
	v_exp_f32_e32 v250, v250
	v_exp_f32_e32 v150, v150
	v_exp_f32_e32 v151, v151
	v_exp_f32_e32 v152, v152
	v_exp_f32_e32 v153, v153
	v_exp_f32_e32 v146, v146
	v_exp_f32_e32 v147, v147
	v_exp_f32_e32 v148, v148
	v_exp_f32_e32 v149, v149
	v_mov_b32_e32 v247, v225
	v_add_f32_e32 v226, v150, v151
	v_add_f32_e32 v226, v226, v152
	v_add_f32_e32 v226, v226, v153
	v_add_f32_e32 v226, v226, v146
	v_add_f32_e32 v226, v226, v147
	v_add_f32_e32 v226, v226, v148
	v_add_f32_e32 v226, v226, v149
	v_fma_f32 v216, v216, v250, v226
	v_pk_mul_f32 v[32:33], v[32:33], v[250:251] op_sel_hi:[1,0]
	v_pk_mul_f32 v[30:31], v[30:31], v[250:251] op_sel_hi:[1,0]
	v_pk_mul_f32 v[28:29], v[28:29], v[250:251] op_sel_hi:[1,0]
	v_pk_mul_f32 v[26:27], v[26:27], v[250:251] op_sel_hi:[1,0]
	v_pk_mul_f32 v[24:25], v[24:25], v[250:251] op_sel_hi:[1,0]
	v_pk_mul_f32 v[22:23], v[22:23], v[250:251] op_sel_hi:[1,0]
	v_pk_mul_f32 v[20:21], v[20:21], v[250:251] op_sel_hi:[1,0]
	v_pk_mul_f32 v[18:19], v[18:19], v[250:251] op_sel_hi:[1,0]
	v_cvt_pk_bf16_f32 v150, v150, v151
	v_cvt_pk_bf16_f32 v151, v152, v153
	v_cvt_pk_bf16_f32 v152, v146, v147
	v_cvt_pk_bf16_f32 v153, v148, v149
	s_nop 1
	v_mfma_f32_16x16x32_bf16 v[30:33], v[142:145], v[150:153], v[30:33]
	v_mfma_f32_16x16x32_bf16 v[26:29], v[134:137], v[150:153], v[26:29]
	v_mfma_f32_16x16x32_bf16 v[22:25], v[138:141], v[150:153], v[22:25]
	v_mfma_f32_16x16x32_bf16 v[18:21], v[130:133], v[150:153], v[18:21]
	s_add_i32 s24, s92, s90
	s_cmp_gt_u32 s24, 7
	s_cbranch_scc1 .LBB0_556
; __device__ __forceinline__ void attn_phase(const bf16* __restrict__ proj, const bf16* __restrict__ vt, bf16* __restrict__ ya, const float* __restrict__ rpb, int T, int vcu, int G, LAS unsigned char* lds) {
;     ...
;                 for (int j = 0; j < 4; ++j) { const int kr = ka - rsj[j];
;                     if (kr >= 0 && kr < 8) {
;                         f32x4 st[2];
; #pragma unroll
;                         for (int hf = 0; hf < 2; ++hf) { const f32x4 t = __builtin_amdgcn_mfma_f32_16x16x32_bf16(kf[hf][0], qf[j][0], (f32x4){0.f, 0.f, 0.f, 0.f}, 0, 0, 0);
;                             st[hf] = __builtin_amdgcn_mfma_f32_16x16x32_bf16(kf[hf][1], qf[j][1], t, 0, 0, 0); }
;                         const LAS float* tb = tbh + (ka - i0 - j + 7) * 31;
;                         float mloc = -INFINITY;
; #pragma unroll
;                         for (int hf = 0; hf < 2; ++hf)
; #pragma unroll
;                             for (int e = 0; e < 4; ++e) { const unsigned dc = ((hf == 0 ? dpack0 : dpack1) >> (8 * e)) & 0xffu; const float b = tb[dc];
;                                 const float v = ((vmask >> (hf * 4 + e)) & 1u) ? st[hf][e] * SC + b : -INFINITY; st[hf][e] = v; mloc = fmaxf(mloc, v); }
;                         mloc = fmaxf(mloc, __shfl_xor(mloc, 16)); mloc = fmaxf(mloc, __shfl_xor(mloc, 32));
;                         const float mnew = fmaxf(mrun[j], mloc), alpha = __builtin_amdgcn_exp2f(mrun[j] - mnew); mrun[j] = mnew;
;                         float p[8], psum = 0.f;
; #pragma unroll
;                         for (int hf = 0; hf < 2; ++hf)
; #pragma unroll
;                             for (int e = 0; e < 4; ++e) { p[hf * 4 + e] = __builtin_amdgcn_exp2f(st[hf][e] - mnew); psum += p[hf * 4 + e]; }
;                         lrun[j] = lrun[j] * alpha + psum;
;                         v4u w; w.x = cvt_pk_bf16(p[0], p[1]); w.y = cvt_pk_bf16(p[2], p[3]); w.z = cvt_pk_bf16(p[4], p[5]); w.w = cvt_pk_bf16(p[6], p[7]);
;                         const bf16x8 pk = __builtin_bit_cast(bf16x8, w);
; #pragma unroll
;                         for (int dt = 0; dt < 4; ++dt) o[j][dt] = __builtin_amdgcn_mfma_f32_16x16x32_bf16(__builtin_bit_cast(bf16x8, vf[dt]), pk, o[j][dt] * alpha, 0, 0, 0);
;                     } }
; #pragma unroll
;                 for (int hf = 0; hf < 2; ++hf) { kf[hf][0] = kn[hf][0]; kf[hf][1] = kn[hf][1]; }
;             }
.LBB0_539:
	v_add_u32_e32 v251, s91, v245
	v_add_u32_e32 v250, s91, v244
	v_add_u32_e32 v227, s91, v243
	v_add_u32_e32 v226, s91, v242
	v_add_u32_e32 v199, s91, v241
	v_add_u32_e32 v212, s91, v240
	v_add_u32_e32 v213, s91, v239
	v_add_u32_e32 v214, s91, v238
	ds_read_b32 v251, v251
	ds_read_b32 v250, v250
	ds_read_b32 v227, v227
	ds_read_b32 v226, v226
	ds_read_b32 v199, v199
	ds_read_b32 v212, v212
	ds_read_b32 v213, v213
	ds_read_b32 v214, v214
	v_mfma_f32_16x16x32_bf16 v[118:121], v[118:121], v[90:93], 0
	v_mfma_f32_16x16x32_bf16 v[118:121], v[122:125], v[94:97], v[118:121]
	v_mfma_f32_16x16x32_bf16 v[124:127], v[126:129], v[90:93], 0
	v_mfma_f32_16x16x32_bf16 v[110:113], v[110:113], v[94:97], v[124:127]
	v_mov_b32_e32 v184, 0xff800000
	s_nop 6
	s_waitcnt lgkmcnt(0)
	v_fmamk_f32 v118, v118, 0x3e38aa3b, v251
	v_fmamk_f32 v119, v119, 0x3e38aa3b, v250
	v_fmamk_f32 v120, v120, 0x3e38aa3b, v227
	v_fmamk_f32 v121, v121, 0x3e38aa3b, v226
	v_fmamk_f32 v110, v110, 0x3e38aa3b, v199
	v_fmamk_f32 v111, v111, 0x3e38aa3b, v212
	v_fmamk_f32 v112, v112, 0x3e38aa3b, v213
	v_fmamk_f32 v113, v113, 0x3e38aa3b, v214
	v_cndmask_b32_e64 v118, v184, v118, s[38:39]
	v_cndmask_b32_e64 v119, v184, v119, s[40:41]
	v_cndmask_b32_e64 v120, v184, v120, s[42:43]
	v_cndmask_b32_e64 v121, v184, v121, s[44:45]
	v_cndmask_b32_e64 v110, v184, v110, s[46:47]
	v_cndmask_b32_e64 v111, v184, v111, s[48:49]
	v_cndmask_b32_e64 v112, v184, v112, s[50:51]
	v_cndmask_b32_e64 v113, v184, v113, s[52:53]
	v_max3_f32 v225, v118, v119, v120
	v_max3_f32 v225, v225, v121, v110
	v_max3_f32 v225, v225, v111, v112
	v_max_f32_e32 v225, v225, v113
	v_mov_b32_e32 v226, v225
	s_nop 1
	v_permlane16_swap_b32_e32 v225, v226
	v_max_f32_e32 v225, v225, v226
	v_mov_b32_e32 v226, v225
	s_nop 1
	v_permlane32_swap_b32_e32 v225, v226
	v_max3_f32 v225, v246, v225, v226
	v_sub_f32_e32 v250, v246, v225
	v_sub_f32_e32 v118, v118, v225
	v_sub_f32_e32 v119, v119, v225
	v_sub_f32_e32 v120, v120, v225
	v_sub_f32_e32 v121, v121, v225
	v_sub_f32_e32 v110, v110, v225
	v_sub_f32_e32 v111, v111, v225
	v_sub_f32_e32 v112, v112, v225
	v_sub_f32_e32 v113, v113, v225
	v_exp_f32_e32 v250, v250
	v_exp_f32_e32 v118, v118
	v_exp_f32_e32 v119, v119
	v_exp_f32_e32 v120, v120
	v_exp_f32_e32 v121, v121
	v_exp_f32_e32 v110, v110
	v_exp_f32_e32 v111, v111
	v_exp_f32_e32 v112, v112
	v_exp_f32_e32 v113, v113
	v_mov_b32_e32 v246, v225
	v_add_f32_e32 v226, v118, v119
	v_add_f32_e32 v226, v226, v120
	v_add_f32_e32 v226, v226, v121
	v_add_f32_e32 v226, v226, v110
	v_add_f32_e32 v226, v226, v111
	v_add_f32_e32 v226, v226, v112
	v_add_f32_e32 v226, v226, v113
	v_fma_f32 v215, v215, v250, v226
	v_pk_mul_f32 v[16:17], v[16:17], v[250:251] op_sel_hi:[1,0]
	v_pk_mul_f32 v[14:15], v[14:15], v[250:251] op_sel_hi:[1,0]
	v_pk_mul_f32 v[12:13], v[12:13], v[250:251] op_sel_hi:[1,0]
	v_pk_mul_f32 v[10:11], v[10:11], v[250:251] op_sel_hi:[1,0]
	v_pk_mul_f32 v[8:9], v[8:9], v[250:251] op_sel_hi:[1,0]
	v_pk_mul_f32 v[6:7], v[6:7], v[250:251] op_sel_hi:[1,0]
	v_pk_mul_f32 v[4:5], v[4:5], v[250:251] op_sel_hi:[1,0]
	v_pk_mul_f32 v[2:3], v[2:3], v[250:251] op_sel_hi:[1,0]
	v_cvt_pk_bf16_f32 v118, v118, v119
	v_cvt_pk_bf16_f32 v119, v120, v121
	v_cvt_pk_bf16_f32 v120, v110, v111
	v_cvt_pk_bf16_f32 v121, v112, v113
	s_nop 1
	v_mfma_f32_16x16x32_bf16 v[14:17], v[142:145], v[118:121], v[14:17]
	v_mfma_f32_16x16x32_bf16 v[10:13], v[134:137], v[118:121], v[10:13]
	v_mfma_f32_16x16x32_bf16 v[6:9], v[138:141], v[118:121], v[6:9]
	v_mfma_f32_16x16x32_bf16 v[2:5], v[130:133], v[118:121], v[2:5]
.LBB0_556:
	s_add_i32 s90, s90, 1
	v_add_u32_e32 v219, 0x7c, v219
	v_add_u32_e32 v220, 0x7c, v220
	v_add_u32_e32 v221, 0x7c, v221
	v_add_u32_e32 v233, 0x7c, v233
	v_add_u32_e32 v234, 0x7c, v234
	v_add_u32_e32 v235, 0x7c, v235
	v_add_u32_e32 v236, 0x7c, v236
	v_add_u32_e32 v237, 0x7c, v237
	v_add_u32_e32 v238, 0x7c, v238
	v_add_u32_e32 v239, 0x7c, v239
	v_add_u32_e32 v240, 0x7c, v240
	v_add_u32_e32 v241, 0x7c, v241
	v_add_u32_e32 v242, 0x7c, v242
	v_add_u32_e32 v243, 0x7c, v243
	v_add_u32_e32 v244, 0x7c, v244
	v_add_u32_e32 v245, 0x7c, v245
.Lattn_skip:
	s_add_i32 s77, s77, 1
	s_cmp_le_i32 s77, s78
	s_cbranch_scc1 .Lattn_step
	s_barrier
	v_readlane_b32 s28, v253, 50
	v_readlane_b32 s29, v253, 51
	v_readlane_b32 s62, v253, 52
	v_readlane_b32 s63, v253, 53
	s_nop 4
